# P3b tile transition: no wait for the epilogue's stores before the next tile's prefetched K-tiles are moved into place
# baseline (speedup 1.0000x reference)
; DI void phase3b(const Params& p, unsigned char* smem, int tid) {
;     ...
;     for (int rb = 0; rb < 16 * 64; rb += per_round) {
;         const int idp = rb + xcd * (per_round >> 3) + cu;
;         const bool v = vn;
;         const bf16_t* P = Pn; const bf16_t* Q = Qn;
;         if (!v) { vn = tile_ptrs(rb + per_round, Pn, Qn); if (vn) { int ti = tid; asm volatile("" : "+v"(ti)); gemm_issue(Pn, Qn, gs, ti); } continue; }
.Lp3b_912n:
	v_mov_b64_e32 v[32:33], v[140:141]
	v_mov_b64_e32 v[36:37], v[136:137]
	v_mov_b64_e32 v[40:41], v[132:133]
	v_mov_b64_e32 v[44:45], v[128:129]
	v_mov_b64_e32 v[34:35], v[142:143]
	v_mov_b64_e32 v[38:39], v[138:139]
	s_mov_b64 s[24:25], s[8:9]
	s_mov_b64 s[22:23], s[6:7]
	v_mov_b64_e32 v[42:43], v[134:135]
	v_mov_b64_e32 v[46:47], v[130:131]
	s_branch .Lp3b_913n

; DI void phase3b(const Params& p, unsigned char* smem, int tid) {
;     ...
;     for (int rb = 0; rb < 16 * 64; rb += per_round) {
;         const int idp = rb + xcd * (per_round >> 3) + cu;
;         const bool v = vn;
;         const bf16_t* P = Pn; const bf16_t* Q = Qn;
;         if (!v) { vn = tile_ptrs(rb + per_round, Pn, Qn); if (vn) { int ti = tid; asm volatile("" : "+v"(ti)); gemm_issue(Pn, Qn, gs, ti); } continue; }
.Lp3b_913n:
	v_mov_b64_e32 v[142:143], v[34:35]
	v_mov_b64_e32 v[138:139], v[38:39]
	v_mov_b64_e32 v[16:17], v[144:145]
	v_mov_b64_e32 v[24:25], v[152:153]
	v_mov_b64_e32 v[20:21], v[148:149]
	v_mov_b64_e32 v[28:29], v[156:157]
	v_mov_b64_e32 v[0:1], v[160:161]
	v_mov_b64_e32 v[12:13], v[164:165]
	v_mov_b64_e32 v[4:5], v[168:169]
	v_mov_b64_e32 v[8:9], v[172:173]
	v_mov_b64_e32 v[134:135], v[42:43]
	v_mov_b64_e32 v[130:131], v[46:47]
	s_cmpk_lt_i32 s38, 0x400
	s_mov_b32 s14, s38
	v_mov_b64_e32 v[140:141], v[32:33]
	v_mov_b64_e32 v[136:137], v[36:37]
	s_mov_b64 s[8:9], s[24:25]
	s_mov_b64 s[6:7], s[22:23]
	v_mov_b64_e32 v[18:19], v[146:147]
	v_mov_b64_e32 v[26:27], v[154:155]
	v_mov_b64_e32 v[22:23], v[150:151]
	v_mov_b64_e32 v[30:31], v[158:159]
	v_mov_b64_e32 v[2:3], v[162:163]
	v_mov_b64_e32 v[14:15], v[166:167]
	v_mov_b64_e32 v[6:7], v[170:171]
	v_mov_b64_e32 v[10:11], v[174:175]
	v_mov_b64_e32 v[132:133], v[40:41]
	v_mov_b64_e32 v[128:129], v[44:45]
	s_cbranch_scc0 .LBB0_934

; DI unsigned pk2(float lo, float hi) { f32x2 v = {lo, hi}; bf2_t b = __builtin_convertvector(v, bf2_t); return __builtin_bit_cast(unsigned, b); }
; DI u32x2 pk4(float a, float b, float c, float d) { u32x2 r; r.x = pk2(a, b); r.y = pk2(c, d); return r; }
; DI float bf_lo(unsigned u) { return __uint_as_float(u << 16); }
; DI float bf_hi(unsigned u) { return __uint_as_float(u & 0xffff0000u); }
; template <int WI, int WGJ, class GetF, class LdF, class FinF>
; DI void staged_rows_rmw(unsigned char* lds, int tid, GetF get, LdF ld, FinF fin) {
;     constexpr int WGI = 8 / WGJ, BI = WGI * WI * 32, RS = BI * 2 + 16, ROWS = WGJ * 32, NCH = BI / 8, NIT = ROWS * NCH / NT;
;     const int lane = tid & 63, wid = tid >> 6, wi = wid / WGJ, wj = wid % WGJ, h = lane >> 5, ln = lane & 31;
; #pragma unroll
;     for (int jt = 0; jt < 2; ++jt) {
;         unsigned char* wrow = lds + (wj * 32 + ln) * RS + (wi * WI * 32 + 4 * h) * 2;
; #pragma unroll
;         for (int it = 0; it < WI; ++it)
; #pragma unroll
;             for (int g = 0; g < 4; ++g) *(u32x2*)(wrow + (it * 32 + 8 * g) * 2) = get(it, jt, g);
;         constexpr int NGRP = 2, GSZ = NIT / NGRP;
;         __syncthreads();
; #pragma unroll 1
;         for (int gq = 0; gq < NGRP; ++gq) {
;             decltype(ld(0, 0)) fetched[GSZ];
; #pragma unroll
;             for (int c = 0; c < GSZ; ++c) {
;                 const int idx = tid + (gq * GSZ + c) * NT, lr = idx / NCH, ch = idx % NCH;
;                 fetched[c] = ld((lr >> 5) * 64 + jt * 32 + (lr & 31), ch * 8);
; DI void phase3b(const Params& p, unsigned char* smem, int tid) {
;     ...
;         if (half == 0) {
;             bf16_t* obuf = (bf16_t*)(ws + (f < 4 ? OFF_QN : OFF_FQ)) + (f & 3) * 256;
;             staged_rows_rmw<4, 4>(lds, te,
;                 [&](int it, int jt, int g) { const float sc = rsj[jt];
;                     return pk4(fsilu(acc[it][jt][4 * g] * sc), fsilu(acc[it][jt][4 * g + 1] * sc), fsilu(acc[it][jt][4 * g + 2] * sc), fsilu(acc[it][jt][4 * g + 3] * sc)); },
;                 [&](int row, int col) { return *(const u32x4*)(obuf + (size_t)(r0 + row) * 1024 + col); },
;                 [&](int row, int col, u32x4 v, u32x4 o) { u32x4 w;
; #pragma unroll
;                     for (int e = 0; e < 4; ++e) w[e] = pk2(bf_lo(o[e]) * bf_lo(v[e]), bf_hi(o[e]) * bf_hi(v[e]));
;                     *(u32x4*)(obuf + (size_t)(r0 + row) * 1024 + col) = w; });
.LBB0_928:
	s_andn2_b64 vcc, exec, s[22:23]
	s_cbranch_vccnz .Lp3b_912n
	s_cmp_lt_u32 s25, 4
	s_cselect_b32 s98, s36, 0x398fc00
	s_lshr_b32 s99, s24, 2
	s_lshl_b32 s99, s99, 9
	s_and_b32 s99, s99, 0x600
	s_add_u32 s98, s98, s99
	s_add_u32 s100, s56, s98
	s_addc_u32 s101, s57, 0
	v_lshrrev_b32_e32 v196, 5, v177
	v_add_u32_e32 v196, s26, v196
	v_lshlrev_b32_e32 v196, 11, v196
	v_and_b32_e32 v197, 31, v177
	v_lshl_add_u32 v196, v197, 4, v196
	v_lshrrev_b32_e32 v244, 5, v177
	v_mul_u32_u24_e32 v244, 0x210, v244
	v_lshl_add_u32 v197, v197, 4, v244
	global_load_dwordx4 v[188:191], v196, s[100:101]
	v_add_u32_e32 v245, 0x8000, v196
	global_load_dwordx4 v[192:195], v245, s[100:101]
	v_add_u32_e32 v244, 0x20000, v196
	global_load_dwordx4 v[200:203], v244, s[100:101]
	v_add_u32_e32 v245, 0x28000, v196
	global_load_dwordx4 v[204:207], v245, s[100:101]
	v_add_u32_e32 v244, 0x40000, v196
	global_load_dwordx4 v[208:211], v244, s[100:101]
	v_add_u32_e32 v245, 0x48000, v196
	global_load_dwordx4 v[212:215], v245, s[100:101]
	v_add_u32_e32 v244, 0x60000, v196
	global_load_dwordx4 v[216:219], v244, s[100:101]
	v_add_u32_e32 v245, 0x68000, v196
	global_load_dwordx4 v[220:223], v245, s[100:101]
	v_add_u32_e32 v244, 0x10000, v196
	global_load_dwordx4 v[224:227], v244, s[100:101]
	v_add_u32_e32 v245, 0x18000, v196
	global_load_dwordx4 v[228:231], v245, s[100:101]
	v_add_u32_e32 v244, 0x30000, v196
	global_load_dwordx4 v[232:235], v244, s[100:101]
	v_add_u32_e32 v245, 0x38000, v196
	global_load_dwordx4 v[236:239], v245, s[100:101]
	v_lshrrev_b32_e32 v181, 30, v181
	v_add_u32_e32 v181, v180, v181
	v_and_b32_e32 v182, 0x7ffffc, v181
	v_sub_u32_e32 v180, v180, v182
	v_lshl_or_b32 v179, v180, 5, v179
	v_lshlrev_b32_e32 v180, 6, v181
	v_mul_lo_u32 v179, v179, s37
	v_and_b32_e32 v180, 0xffffff00, v180
	v_add3_u32 v179, 0, v179, v180
	s_waitcnt vmcnt(13)
	v_pk_mul_f32 v[112:113], v[112:113], v[178:179] op_sel_hi:[1,0]
	v_lshrrev_b32_e32 v181, 2, v177
	v_mul_f32_e32 v180, 0xbfb8aa3b, v112
	v_mul_f32_e32 v182, 0xbfb8aa3b, v113
	v_exp_f32_e32 v180, v180
	v_exp_f32_e32 v182, v182
	v_and_b32_e32 v181, 8, v181
	v_add_u32_e32 v179, v179, v181
	v_pk_mul_f32 v[114:115], v[114:115], v[178:179] op_sel_hi:[1,0]
	v_add_f32_e32 v180, 1.0, v180
	v_add_f32_e32 v181, 1.0, v182
	v_mul_f32_e32 v182, 0xbfb8aa3b, v114
	v_mul_f32_e32 v183, 0xbfb8aa3b, v115
	v_rcp_f32_e32 v180, v180
	v_rcp_f32_e32 v181, v181
	v_exp_f32_e32 v182, v182
	v_exp_f32_e32 v183, v183
	v_pk_mul_f32 v[116:117], v[116:117], v[178:179] op_sel_hi:[1,0]
	v_pk_mul_f32 v[112:113], v[112:113], v[180:181]
	v_add_f32_e32 v180, 1.0, v182
	v_add_f32_e32 v181, 1.0, v183
	v_mul_f32_e32 v182, 0xbfb8aa3b, v116
	v_mul_f32_e32 v183, 0xbfb8aa3b, v117
	v_rcp_f32_e32 v180, v180
	v_rcp_f32_e32 v181, v181
	v_exp_f32_e32 v182, v182
	v_exp_f32_e32 v183, v183
	v_pk_mul_f32 v[118:119], v[118:119], v[178:179] op_sel_hi:[1,0]
	v_pk_mul_f32 v[114:115], v[114:115], v[180:181]
	v_add_f32_e32 v180, 1.0, v182
	v_add_f32_e32 v181, 1.0, v183
	v_mul_f32_e32 v182, 0xbfb8aa3b, v118
	v_mul_f32_e32 v183, 0xbfb8aa3b, v119
	v_exp_f32_e32 v182, v182
	v_exp_f32_e32 v183, v183
	v_rcp_f32_e32 v180, v180
	v_rcp_f32_e32 v181, v181
	v_add_f32_e32 v182, 1.0, v182
	v_add_f32_e32 v183, 1.0, v183
	v_rcp_f32_e32 v182, v182
	v_rcp_f32_e32 v183, v183
	v_cvt_pk_bf16_f32 v187, v114, v115
	v_cvt_pk_bf16_f32 v186, v112, v113
	v_pk_mul_f32 v[112:113], v[116:117], v[180:181]
	v_pk_mul_f32 v[114:115], v[118:119], v[182:183]
	v_cvt_pk_bf16_f32 v116, v112, v113
	v_cvt_pk_bf16_f32 v117, v114, v115
	v_pk_mul_f32 v[114:115], v[120:121], v[178:179] op_sel_hi:[1,0]
	v_add_u32_e32 v112, 0x800, v179
	v_mul_f32_e32 v113, 0xbfb8aa3b, v114
	v_exp_f32_e32 v113, v113
	v_mul_f32_e32 v118, 0xbfb8aa3b, v115
	v_exp_f32_e32 v118, v118
	ds_write2_b64 v112, v[186:187], v[116:117] offset1:2
	v_add_f32_e32 v113, 1.0, v113
	v_rcp_f32_e32 v116, v113
	v_add_f32_e32 v113, 1.0, v118
	v_pk_mul_f32 v[118:119], v[122:123], v[178:179] op_sel_hi:[1,0]
	v_rcp_f32_e32 v117, v113
	v_mul_f32_e32 v113, 0xbfb8aa3b, v118
	v_exp_f32_e32 v113, v113
	v_mul_f32_e32 v120, 0xbfb8aa3b, v119
	v_exp_f32_e32 v120, v120
	v_pk_mul_f32 v[114:115], v[114:115], v[116:117]
	v_add_f32_e32 v113, 1.0, v113
	v_rcp_f32_e32 v116, v113
	v_add_f32_e32 v113, 1.0, v120
	v_pk_mul_f32 v[120:121], v[124:125], v[178:179] op_sel_hi:[1,0]
	v_rcp_f32_e32 v117, v113
	v_mul_f32_e32 v113, 0xbfb8aa3b, v120
	v_exp_f32_e32 v113, v113
	v_mul_f32_e32 v122, 0xbfb8aa3b, v121
	v_exp_f32_e32 v122, v122
	v_pk_mul_f32 v[116:117], v[118:119], v[116:117]
	v_add_f32_e32 v113, 1.0, v113
	v_rcp_f32_e32 v118, v113
	v_add_f32_e32 v113, 1.0, v122
	v_pk_mul_f32 v[122:123], v[126:127], v[178:179] op_sel_hi:[1,0]
	v_pk_mul_f32 v[96:97], v[96:97], v[178:179] op_sel_hi:[1,0]
	v_mul_f32_e32 v119, 0xbfb8aa3b, v122
	v_exp_f32_e32 v124, v119
	v_mul_f32_e32 v119, 0xbfb8aa3b, v123
	v_exp_f32_e32 v125, v119
	v_rcp_f32_e32 v119, v113
	v_add_f32_e32 v113, 1.0, v124
	v_rcp_f32_e32 v124, v113
	v_add_f32_e32 v113, 1.0, v125
	v_rcp_f32_e32 v125, v113
	v_cvt_pk_bf16_f32 v114, v114, v115
	v_cvt_pk_bf16_f32 v115, v116, v117
	v_pk_mul_f32 v[116:117], v[120:121], v[118:119]
	v_pk_mul_f32 v[118:119], v[122:123], v[124:125]
	v_mul_f32_e32 v113, 0xbfb8aa3b, v96
	v_cvt_pk_bf16_f32 v116, v116, v117
	v_cvt_pk_bf16_f32 v117, v118, v119
	v_exp_f32_e32 v113, v113
	v_mul_f32_e32 v118, 0xbfb8aa3b, v97
	v_exp_f32_e32 v118, v118
	ds_write2_b64 v112, v[114:115], v[116:117] offset0:4 offset1:6
	v_add_f32_e32 v113, 1.0, v113
	v_rcp_f32_e32 v114, v113
	v_add_f32_e32 v113, 1.0, v118
	v_pk_mul_f32 v[98:99], v[98:99], v[178:179] op_sel_hi:[1,0]
	v_rcp_f32_e32 v115, v113
	v_mul_f32_e32 v113, 0xbfb8aa3b, v98
; DI u32x2 pk4(float a, float b, float c, float d) { u32x2 r; r.x = pk2(a, b); r.y = pk2(c, d); return r; }
; DI float fsilu(float z) { return z * fsigmoid(z); }
; template <int WI, int WGJ, class GetF, class LdF, class FinF>
; DI void staged_rows_rmw(unsigned char* lds, int tid, GetF get, LdF ld, FinF fin) {
;     ...
;         for (int it = 0; it < WI; ++it)
; #pragma unroll
;             for (int g = 0; g < 4; ++g) *(u32x2*)(wrow + (it * 32 + 8 * g) * 2) = get(it, jt, g);
; DI void phase3b(const Params& p, unsigned char* smem, int tid) {
;     ...
;                 [&](int it, int jt, int g) { const float sc = rsj[jt];
;                     return pk4(fsilu(acc[it][jt][4 * g] * sc), fsilu(acc[it][jt][4 * g + 1] * sc), fsilu(acc[it][jt][4 * g + 2] * sc), fsilu(acc[it][jt][4 * g + 3] * sc)); },
	v_exp_f32_e32 v113, v113
	v_mul_f32_e32 v116, 0xbfb8aa3b, v99
	v_exp_f32_e32 v116, v116
	v_pk_mul_f32 v[96:97], v[96:97], v[114:115]
	v_add_f32_e32 v113, 1.0, v113
	v_rcp_f32_e32 v114, v113
	v_add_f32_e32 v113, 1.0, v116
	v_pk_mul_f32 v[100:101], v[100:101], v[178:179] op_sel_hi:[1,0]
	v_rcp_f32_e32 v115, v113
	v_mul_f32_e32 v113, 0xbfb8aa3b, v100
	v_exp_f32_e32 v113, v113
	v_mul_f32_e32 v116, 0xbfb8aa3b, v101
	v_exp_f32_e32 v116, v116
	v_pk_mul_f32 v[102:103], v[102:103], v[178:179] op_sel_hi:[1,0]
	v_pk_mul_f32 v[98:99], v[98:99], v[114:115]
	v_add_f32_e32 v113, 1.0, v113
	v_mul_f32_e32 v115, 0xbfb8aa3b, v102
	v_rcp_f32_e32 v114, v113
	v_add_f32_e32 v113, 1.0, v116
	v_exp_f32_e32 v116, v115
	v_mul_f32_e32 v115, 0xbfb8aa3b, v103
	v_exp_f32_e32 v117, v115
	v_rcp_f32_e32 v115, v113
	v_add_f32_e32 v113, 1.0, v116
	v_rcp_f32_e32 v116, v113
	v_add_f32_e32 v113, 1.0, v117
	v_rcp_f32_e32 v117, v113
	v_cvt_pk_bf16_f32 v96, v96, v97
	v_cvt_pk_bf16_f32 v97, v98, v99
	v_pk_mul_f32 v[98:99], v[100:101], v[114:115]
	v_pk_mul_f32 v[100:101], v[102:103], v[116:117]
	v_cvt_pk_bf16_f32 v98, v98, v99
	v_cvt_pk_bf16_f32 v99, v100, v101
	v_pk_mul_f32 v[100:101], v[104:105], v[178:179] op_sel_hi:[1,0]
	ds_write2_b64 v112, v[96:97], v[98:99] offset0:8 offset1:10
	v_mul_f32_e32 v102, 0xbfb8aa3b, v100
	v_mul_f32_e32 v103, 0xbfb8aa3b, v101
	v_exp_f32_e32 v102, v102
	v_exp_f32_e32 v103, v103
	v_pk_mul_f32 v[98:99], v[106:107], v[178:179] op_sel_hi:[1,0]
	v_pk_mul_f32 v[80:81], v[80:81], v[178:179] op_sel_hi:[1,0]
	v_add_f32_e32 v96, 1.0, v102
	v_add_f32_e32 v97, 1.0, v103
	v_mul_f32_e32 v102, 0xbfb8aa3b, v98
	v_mul_f32_e32 v103, 0xbfb8aa3b, v99
	v_rcp_f32_e32 v96, v96
	v_rcp_f32_e32 v97, v97
	v_exp_f32_e32 v102, v102
	v_exp_f32_e32 v103, v103
	v_pk_mul_f32 v[82:83], v[82:83], v[178:179] op_sel_hi:[1,0]
	v_pk_mul_f32 v[96:97], v[100:101], v[96:97]
	v_add_f32_e32 v100, 1.0, v102
	v_add_f32_e32 v101, 1.0, v103
	v_pk_mul_f32 v[102:103], v[108:109], v[178:179] op_sel_hi:[1,0]
	v_rcp_f32_e32 v100, v100
	v_mul_f32_e32 v104, 0xbfb8aa3b, v102
	v_mul_f32_e32 v105, 0xbfb8aa3b, v103
	v_rcp_f32_e32 v101, v101
	v_exp_f32_e32 v104, v104
	v_exp_f32_e32 v105, v105
	v_cvt_pk_bf16_f32 v96, v96, v97
	v_pk_mul_f32 v[98:99], v[98:99], v[100:101]
	v_add_f32_e32 v100, 1.0, v104
	v_add_f32_e32 v101, 1.0, v105
	v_pk_mul_f32 v[104:105], v[110:111], v[178:179] op_sel_hi:[1,0]
	v_rcp_f32_e32 v100, v100
	v_mul_f32_e32 v106, 0xbfb8aa3b, v104
	v_mul_f32_e32 v107, 0xbfb8aa3b, v105
	v_exp_f32_e32 v106, v106
	v_exp_f32_e32 v107, v107
	v_rcp_f32_e32 v101, v101
	v_cvt_pk_bf16_f32 v97, v98, v99
	v_add_f32_e32 v106, 1.0, v106
	v_add_f32_e32 v107, 1.0, v107
	v_rcp_f32_e32 v106, v106
	v_rcp_f32_e32 v107, v107
	v_pk_mul_f32 v[98:99], v[102:103], v[100:101]
	v_pk_mul_f32 v[84:85], v[84:85], v[178:179] op_sel_hi:[1,0]
	v_cvt_pk_bf16_f32 v98, v98, v99
	v_pk_mul_f32 v[100:101], v[104:105], v[106:107]
	v_pk_mul_f32 v[86:87], v[86:87], v[178:179] op_sel_hi:[1,0]
	v_cvt_pk_bf16_f32 v99, v100, v101
	v_mul_f32_e32 v100, 0xbfb8aa3b, v80
	v_mul_f32_e32 v101, 0xbfb8aa3b, v81
	v_exp_f32_e32 v100, v100
	v_exp_f32_e32 v101, v101
	ds_write2_b64 v112, v[96:97], v[98:99] offset0:12 offset1:14
	v_mul_f32_e32 v98, 0xbfb8aa3b, v82
	v_add_f32_e32 v96, 1.0, v100
	v_add_f32_e32 v97, 1.0, v101
	v_mul_f32_e32 v99, 0xbfb8aa3b, v83
	v_rcp_f32_e32 v96, v96
	v_rcp_f32_e32 v97, v97
	v_exp_f32_e32 v98, v98
	v_exp_f32_e32 v99, v99
	v_pk_mul_f32 v[64:65], v[64:65], v[178:179] op_sel_hi:[1,0]
	v_pk_mul_f32 v[80:81], v[80:81], v[96:97]
	v_add_f32_e32 v96, 1.0, v98
	v_add_f32_e32 v97, 1.0, v99
	v_mul_f32_e32 v98, 0xbfb8aa3b, v84
	v_mul_f32_e32 v99, 0xbfb8aa3b, v85
	v_rcp_f32_e32 v96, v96
	v_rcp_f32_e32 v97, v97
	v_exp_f32_e32 v98, v98
	v_exp_f32_e32 v99, v99
	v_cvt_pk_bf16_f32 v80, v80, v81
	v_pk_mul_f32 v[82:83], v[82:83], v[96:97]
	v_add_f32_e32 v96, 1.0, v98
	v_add_f32_e32 v97, 1.0, v99
	v_mul_f32_e32 v98, 0xbfb8aa3b, v86
	v_mul_f32_e32 v99, 0xbfb8aa3b, v87
	v_exp_f32_e32 v98, v98
	v_exp_f32_e32 v99, v99
	v_rcp_f32_e32 v96, v96
	v_rcp_f32_e32 v97, v97
	v_add_f32_e32 v98, 1.0, v98
	v_add_f32_e32 v99, 1.0, v99
	v_rcp_f32_e32 v98, v98
	v_rcp_f32_e32 v99, v99
	v_cvt_pk_bf16_f32 v81, v82, v83
	v_pk_mul_f32 v[82:83], v[84:85], v[96:97]
	v_pk_mul_f32 v[66:67], v[66:67], v[178:179] op_sel_hi:[1,0]
	v_pk_mul_f32 v[84:85], v[86:87], v[98:99]
	v_cvt_pk_bf16_f32 v82, v82, v83
	v_cvt_pk_bf16_f32 v83, v84, v85
	v_pk_mul_f32 v[84:85], v[88:89], v[178:179] op_sel_hi:[1,0]
	ds_write2_b64 v112, v[80:81], v[82:83] offset0:16 offset1:18
	v_mul_f32_e32 v86, 0xbfb8aa3b, v84
	v_mul_f32_e32 v87, 0xbfb8aa3b, v85
	v_exp_f32_e32 v86, v86
	v_exp_f32_e32 v87, v87
	v_pk_mul_f32 v[82:83], v[90:91], v[178:179] op_sel_hi:[1,0]
	v_pk_mul_f32 v[68:69], v[68:69], v[178:179] op_sel_hi:[1,0]
	v_add_f32_e32 v80, 1.0, v86
	v_add_f32_e32 v81, 1.0, v87
	v_mul_f32_e32 v86, 0xbfb8aa3b, v82
	v_mul_f32_e32 v87, 0xbfb8aa3b, v83
	v_rcp_f32_e32 v80, v80
	v_rcp_f32_e32 v81, v81
	v_exp_f32_e32 v86, v86
	v_exp_f32_e32 v87, v87
	v_pk_mul_f32 v[70:71], v[70:71], v[178:179] op_sel_hi:[1,0]
	v_pk_mul_f32 v[80:81], v[84:85], v[80:81]
	v_add_f32_e32 v84, 1.0, v86
	v_add_f32_e32 v85, 1.0, v87
	v_pk_mul_f32 v[86:87], v[92:93], v[178:179] op_sel_hi:[1,0]
	v_rcp_f32_e32 v84, v84
	v_mul_f32_e32 v88, 0xbfb8aa3b, v86
	v_mul_f32_e32 v89, 0xbfb8aa3b, v87
	v_rcp_f32_e32 v85, v85
	v_exp_f32_e32 v88, v88
	v_exp_f32_e32 v89, v89
	v_cvt_pk_bf16_f32 v80, v80, v81
	v_pk_mul_f32 v[82:83], v[82:83], v[84:85]
	v_add_f32_e32 v84, 1.0, v88
	v_add_f32_e32 v85, 1.0, v89
	v_pk_mul_f32 v[88:89], v[94:95], v[178:179] op_sel_hi:[1,0]
	v_rcp_f32_e32 v84, v84
	v_mul_f32_e32 v90, 0xbfb8aa3b, v88
	v_mul_f32_e32 v91, 0xbfb8aa3b, v89
; DI unsigned pk2(float lo, float hi) { f32x2 v = {lo, hi}; bf2_t b = __builtin_convertvector(v, bf2_t); return __builtin_bit_cast(unsigned, b); }
; DI u32x2 pk4(float a, float b, float c, float d) { u32x2 r; r.x = pk2(a, b); r.y = pk2(c, d); return r; }
; DI float bf_lo(unsigned u) { return __uint_as_float(u << 16); }
; DI float bf_hi(unsigned u) { return __uint_as_float(u & 0xffff0000u); }
; DI float fsilu(float z) { return z * fsigmoid(z); }
; template <int WI, int WGJ, class GetF, class LdF, class FinF>
; DI void staged_rows_rmw(unsigned char* lds, int tid, GetF get, LdF ld, FinF fin) {
;     ...
;             for (int g = 0; g < 4; ++g) *(u32x2*)(wrow + (it * 32 + 8 * g) * 2) = get(it, jt, g);
;         constexpr int NGRP = 2, GSZ = NIT / NGRP;
;         __syncthreads();
; #pragma unroll 1
;         for (int gq = 0; gq < NGRP; ++gq) {
;             decltype(ld(0, 0)) fetched[GSZ];
; #pragma unroll
;             for (int c = 0; c < GSZ; ++c) {
;                 const int idx = tid + (gq * GSZ + c) * NT, lr = idx / NCH, ch = idx % NCH;
;                 fetched[c] = ld((lr >> 5) * 64 + jt * 32 + (lr & 31), ch * 8);
;             }
; #pragma unroll
;             for (int c = 0; c < GSZ; ++c) {
;                 const int idx = tid + (gq * GSZ + c) * NT, lr = idx / NCH, ch = idx % NCH;
;                 const u32x4 v = *(const u32x4*)(lds + lr * RS + ch * 16);
;                 fin((lr >> 5) * 64 + jt * 32 + (lr & 31), ch * 8, v, fetched[c]);
; DI void phase3b(const Params& p, unsigned char* smem, int tid) {
;     ...
;                 [&](int it, int jt, int g) { const float sc = rsj[jt];
;                     return pk4(fsilu(acc[it][jt][4 * g] * sc), fsilu(acc[it][jt][4 * g + 1] * sc), fsilu(acc[it][jt][4 * g + 2] * sc), fsilu(acc[it][jt][4 * g + 3] * sc)); },
;                 [&](int row, int col) { return *(const u32x4*)(obuf + (size_t)(r0 + row) * 1024 + col); },
;                 [&](int row, int col, u32x4 v, u32x4 o) { u32x4 w;
; #pragma unroll
;                     for (int e = 0; e < 4; ++e) w[e] = pk2(bf_lo(o[e]) * bf_lo(v[e]), bf_hi(o[e]) * bf_hi(v[e]));
;                     *(u32x4*)(obuf + (size_t)(r0 + row) * 1024 + col) = w; });
	v_exp_f32_e32 v90, v90
	v_exp_f32_e32 v91, v91
	v_rcp_f32_e32 v85, v85
	v_cvt_pk_bf16_f32 v81, v82, v83
	v_add_f32_e32 v90, 1.0, v90
	v_add_f32_e32 v91, 1.0, v91
	v_rcp_f32_e32 v90, v90
	v_rcp_f32_e32 v91, v91
	v_pk_mul_f32 v[82:83], v[86:87], v[84:85]
	s_lshr_b32 s22, s24, 2
	v_cvt_pk_bf16_f32 v82, v82, v83
	v_pk_mul_f32 v[84:85], v[88:89], v[90:91]
	s_cmp_lt_u32 s25, 4
	v_cvt_pk_bf16_f32 v83, v84, v85
	v_mul_f32_e32 v84, 0xbfb8aa3b, v64
	v_mul_f32_e32 v85, 0xbfb8aa3b, v65
	v_exp_f32_e32 v84, v84
	v_exp_f32_e32 v85, v85
	ds_write2_b64 v112, v[80:81], v[82:83] offset0:20 offset1:22
	v_mul_f32_e32 v82, 0xbfb8aa3b, v66
	v_add_f32_e32 v80, 1.0, v84
	v_add_f32_e32 v81, 1.0, v85
	v_mul_f32_e32 v83, 0xbfb8aa3b, v67
	v_rcp_f32_e32 v80, v80
	v_rcp_f32_e32 v81, v81
	v_exp_f32_e32 v82, v82
	v_exp_f32_e32 v83, v83
	s_cselect_b32 s23, s36, 0x398fc00
	v_pk_mul_f32 v[64:65], v[64:65], v[80:81]
	v_add_f32_e32 v80, 1.0, v82
	v_add_f32_e32 v81, 1.0, v83
	v_mul_f32_e32 v82, 0xbfb8aa3b, v68
	v_mul_f32_e32 v83, 0xbfb8aa3b, v69
	v_rcp_f32_e32 v80, v80
	v_rcp_f32_e32 v81, v81
	v_exp_f32_e32 v82, v82
	v_exp_f32_e32 v83, v83
	v_cvt_pk_bf16_f32 v64, v64, v65
	v_pk_mul_f32 v[66:67], v[66:67], v[80:81]
	v_add_f32_e32 v80, 1.0, v82
	v_add_f32_e32 v81, 1.0, v83
	v_mul_f32_e32 v82, 0xbfb8aa3b, v70
	v_mul_f32_e32 v83, 0xbfb8aa3b, v71
	v_exp_f32_e32 v82, v82
	v_exp_f32_e32 v83, v83
	v_rcp_f32_e32 v80, v80
	v_rcp_f32_e32 v81, v81
	v_add_f32_e32 v82, 1.0, v82
	v_add_f32_e32 v83, 1.0, v83
	v_rcp_f32_e32 v82, v82
	v_rcp_f32_e32 v83, v83
	v_cvt_pk_bf16_f32 v65, v66, v67
	v_pk_mul_f32 v[66:67], v[68:69], v[80:81]
	s_add_u32 s23, s56, s23
	v_pk_mul_f32 v[68:69], v[70:71], v[82:83]
	v_cvt_pk_bf16_f32 v66, v66, v67
	v_cvt_pk_bf16_f32 v67, v68, v69
	v_pk_mul_f32 v[68:69], v[72:73], v[178:179] op_sel_hi:[1,0]
	ds_write2_b64 v112, v[64:65], v[66:67] offset0:24 offset1:26
	v_mul_f32_e32 v70, 0xbfb8aa3b, v68
	v_mul_f32_e32 v71, 0xbfb8aa3b, v69
	v_exp_f32_e32 v70, v70
	v_exp_f32_e32 v71, v71
	v_pk_mul_f32 v[66:67], v[74:75], v[178:179] op_sel_hi:[1,0]
	s_addc_u32 s24, s57, 0
	v_add_f32_e32 v64, 1.0, v70
	v_add_f32_e32 v65, 1.0, v71
	v_mul_f32_e32 v70, 0xbfb8aa3b, v66
	v_mul_f32_e32 v71, 0xbfb8aa3b, v67
	v_rcp_f32_e32 v64, v64
	v_rcp_f32_e32 v65, v65
	v_exp_f32_e32 v70, v70
	v_exp_f32_e32 v71, v71
	s_lshl_b32 s22, s22, 9
	v_pk_mul_f32 v[64:65], v[68:69], v[64:65]
	v_add_f32_e32 v68, 1.0, v70
	v_add_f32_e32 v69, 1.0, v71
	v_pk_mul_f32 v[70:71], v[76:77], v[178:179] op_sel_hi:[1,0]
	v_rcp_f32_e32 v68, v68
	v_mul_f32_e32 v72, 0xbfb8aa3b, v70
	v_mul_f32_e32 v73, 0xbfb8aa3b, v71
	v_rcp_f32_e32 v69, v69
	v_exp_f32_e32 v72, v72
	v_exp_f32_e32 v73, v73
	s_and_b32 s22, s22, 0x600
	v_pk_mul_f32 v[66:67], v[66:67], v[68:69]
	v_add_f32_e32 v68, 1.0, v72
	v_add_f32_e32 v69, 1.0, v73
	v_pk_mul_f32 v[72:73], v[78:79], v[178:179] op_sel_hi:[1,0]
	v_rcp_f32_e32 v68, v68
	v_mul_f32_e32 v74, 0xbfb8aa3b, v72
	v_mul_f32_e32 v75, 0xbfb8aa3b, v73
	v_exp_f32_e32 v74, v74
	v_exp_f32_e32 v75, v75
	v_rcp_f32_e32 v69, v69
	s_add_u32 s22, s23, s22
	v_add_f32_e32 v74, 1.0, v74
	v_add_f32_e32 v75, 1.0, v75
	v_rcp_f32_e32 v74, v74
	v_rcp_f32_e32 v75, v75
	v_cvt_pk_bf16_f32 v64, v64, v65
	v_cvt_pk_bf16_f32 v65, v66, v67
	v_pk_mul_f32 v[66:67], v[70:71], v[68:69]
	v_pk_mul_f32 v[68:69], v[72:73], v[74:75]
	s_mov_b32 s14, 0
	s_addc_u32 s23, s24, 0
	v_cvt_pk_bf16_f32 v66, v66, v67
	v_cvt_pk_bf16_f32 v67, v68, v69
	s_mov_b64 s[24:25], -1
	ds_write2_b64 v112, v[64:65], v[66:67] offset0:28 offset1:30
	s_waitcnt lgkmcnt(0)
	s_barrier
	ds_read_b128 v[64:67], v197 offset:2048
	ds_read_b128 v[68:71], v197 offset:10496
	ds_read_b128 v[72:75], v197 offset:18944
	ds_read_b128 v[76:79], v197 offset:27392
	s_waitcnt lgkmcnt(3)
	v_lshlrev_b32_e32 v80, 16, v64
	v_and_b32_e32 v81, 0xffff0000, v64
	v_lshlrev_b32_e32 v82, 16, v65
	v_and_b32_e32 v83, 0xffff0000, v65
	v_lshlrev_b32_e32 v84, 16, v66
	v_and_b32_e32 v85, 0xffff0000, v66
	v_lshlrev_b32_e32 v86, 16, v67
	v_and_b32_e32 v87, 0xffff0000, v67
	s_waitcnt vmcnt(11)
	v_lshlrev_b32_e32 v88, 16, v188
	v_and_b32_e32 v89, 0xffff0000, v188
	v_lshlrev_b32_e32 v90, 16, v189
	v_and_b32_e32 v91, 0xffff0000, v189
	v_lshlrev_b32_e32 v92, 16, v190
	v_and_b32_e32 v93, 0xffff0000, v190
	v_lshlrev_b32_e32 v94, 16, v191
	v_and_b32_e32 v95, 0xffff0000, v191
	v_pk_mul_f32 v[88:89], v[88:89], v[80:81]
	v_pk_mul_f32 v[90:91], v[90:91], v[82:83]
	v_pk_mul_f32 v[92:93], v[92:93], v[84:85]
	v_pk_mul_f32 v[94:95], v[94:95], v[86:87]
	v_cvt_pk_bf16_f32 v188, v88, v89
	v_cvt_pk_bf16_f32 v189, v90, v91
	v_cvt_pk_bf16_f32 v190, v92, v93
	v_cvt_pk_bf16_f32 v191, v94, v95
	global_store_dwordx4 v196, v[188:191], s[100:101]
	s_waitcnt lgkmcnt(2)
	v_lshlrev_b32_e32 v80, 16, v68
	v_and_b32_e32 v81, 0xffff0000, v68
	v_lshlrev_b32_e32 v82, 16, v69
	v_and_b32_e32 v83, 0xffff0000, v69
	v_lshlrev_b32_e32 v84, 16, v70
	v_and_b32_e32 v85, 0xffff0000, v70
	v_lshlrev_b32_e32 v86, 16, v71
	v_and_b32_e32 v87, 0xffff0000, v71
	s_waitcnt vmcnt(11)
	v_lshlrev_b32_e32 v88, 16, v192
	v_and_b32_e32 v89, 0xffff0000, v192
	v_lshlrev_b32_e32 v90, 16, v193
	v_and_b32_e32 v91, 0xffff0000, v193
	v_lshlrev_b32_e32 v92, 16, v194
	v_and_b32_e32 v93, 0xffff0000, v194
	v_lshlrev_b32_e32 v94, 16, v195
	v_and_b32_e32 v95, 0xffff0000, v195
	v_pk_mul_f32 v[88:89], v[88:89], v[80:81]
	v_pk_mul_f32 v[90:91], v[90:91], v[82:83]
	v_pk_mul_f32 v[92:93], v[92:93], v[84:85]
	v_pk_mul_f32 v[94:95], v[94:95], v[86:87]
	v_cvt_pk_bf16_f32 v192, v88, v89
	v_cvt_pk_bf16_f32 v193, v90, v91
	v_cvt_pk_bf16_f32 v194, v92, v93
	v_cvt_pk_bf16_f32 v195, v94, v95
	v_add_u32_e32 v245, 0x8000, v196
	global_store_dwordx4 v245, v[192:195], s[100:101]
	s_waitcnt lgkmcnt(1)
; DI unsigned pk2(float lo, float hi) { f32x2 v = {lo, hi}; bf2_t b = __builtin_convertvector(v, bf2_t); return __builtin_bit_cast(unsigned, b); }
; DI float bf_lo(unsigned u) { return __uint_as_float(u << 16); }
; DI float bf_hi(unsigned u) { return __uint_as_float(u & 0xffff0000u); }
; template <int WI, int WGJ, class GetF, class LdF, class FinF>
; DI void staged_rows_rmw(unsigned char* lds, int tid, GetF get, LdF ld, FinF fin) {
;     ...
;         for (int gq = 0; gq < NGRP; ++gq) {
;             decltype(ld(0, 0)) fetched[GSZ];
; #pragma unroll
;             for (int c = 0; c < GSZ; ++c) {
;                 const int idx = tid + (gq * GSZ + c) * NT, lr = idx / NCH, ch = idx % NCH;
;                 fetched[c] = ld((lr >> 5) * 64 + jt * 32 + (lr & 31), ch * 8);
;             }
; #pragma unroll
;             for (int c = 0; c < GSZ; ++c) {
;                 const int idx = tid + (gq * GSZ + c) * NT, lr = idx / NCH, ch = idx % NCH;
;                 const u32x4 v = *(const u32x4*)(lds + lr * RS + ch * 16);
;                 fin((lr >> 5) * 64 + jt * 32 + (lr & 31), ch * 8, v, fetched[c]);
; DI void phase3b(const Params& p, unsigned char* smem, int tid) {
;     ...
;                 [&](int row, int col) { return *(const u32x4*)(obuf + (size_t)(r0 + row) * 1024 + col); },
;                 [&](int row, int col, u32x4 v, u32x4 o) { u32x4 w;
; #pragma unroll
;                     for (int e = 0; e < 4; ++e) w[e] = pk2(bf_lo(o[e]) * bf_lo(v[e]), bf_hi(o[e]) * bf_hi(v[e]));
;                     *(u32x4*)(obuf + (size_t)(r0 + row) * 1024 + col) = w; });
	v_lshlrev_b32_e32 v80, 16, v72
	v_and_b32_e32 v81, 0xffff0000, v72
	v_lshlrev_b32_e32 v82, 16, v73
	v_and_b32_e32 v83, 0xffff0000, v73
	v_lshlrev_b32_e32 v84, 16, v74
	v_and_b32_e32 v85, 0xffff0000, v74
	v_lshlrev_b32_e32 v86, 16, v75
	v_and_b32_e32 v87, 0xffff0000, v75
	s_waitcnt vmcnt(11)
	v_lshlrev_b32_e32 v88, 16, v200
	v_and_b32_e32 v89, 0xffff0000, v200
	v_lshlrev_b32_e32 v90, 16, v201
	v_and_b32_e32 v91, 0xffff0000, v201
	v_lshlrev_b32_e32 v92, 16, v202
	v_and_b32_e32 v93, 0xffff0000, v202
	v_lshlrev_b32_e32 v94, 16, v203
	v_and_b32_e32 v95, 0xffff0000, v203
	v_pk_mul_f32 v[88:89], v[88:89], v[80:81]
	v_pk_mul_f32 v[90:91], v[90:91], v[82:83]
	v_pk_mul_f32 v[92:93], v[92:93], v[84:85]
	v_pk_mul_f32 v[94:95], v[94:95], v[86:87]
	v_cvt_pk_bf16_f32 v200, v88, v89
	v_cvt_pk_bf16_f32 v201, v90, v91
	v_cvt_pk_bf16_f32 v202, v92, v93
	v_cvt_pk_bf16_f32 v203, v94, v95
	v_add_u32_e32 v244, 0x20000, v196
	global_store_dwordx4 v244, v[200:203], s[100:101]
	s_waitcnt lgkmcnt(0)
	v_lshlrev_b32_e32 v80, 16, v76
	v_and_b32_e32 v81, 0xffff0000, v76
	v_lshlrev_b32_e32 v82, 16, v77
	v_and_b32_e32 v83, 0xffff0000, v77
	v_lshlrev_b32_e32 v84, 16, v78
	v_and_b32_e32 v85, 0xffff0000, v78
	v_lshlrev_b32_e32 v86, 16, v79
	v_and_b32_e32 v87, 0xffff0000, v79
	s_waitcnt vmcnt(11)
	v_lshlrev_b32_e32 v88, 16, v204
	v_and_b32_e32 v89, 0xffff0000, v204
	v_lshlrev_b32_e32 v90, 16, v205
	v_and_b32_e32 v91, 0xffff0000, v205
	v_lshlrev_b32_e32 v92, 16, v206
	v_and_b32_e32 v93, 0xffff0000, v206
	v_lshlrev_b32_e32 v94, 16, v207
	v_and_b32_e32 v95, 0xffff0000, v207
	v_pk_mul_f32 v[88:89], v[88:89], v[80:81]
	v_pk_mul_f32 v[90:91], v[90:91], v[82:83]
	v_pk_mul_f32 v[92:93], v[92:93], v[84:85]
	v_pk_mul_f32 v[94:95], v[94:95], v[86:87]
	v_cvt_pk_bf16_f32 v204, v88, v89
	v_cvt_pk_bf16_f32 v205, v90, v91
	v_cvt_pk_bf16_f32 v206, v92, v93
	v_cvt_pk_bf16_f32 v207, v94, v95
	v_add_u32_e32 v245, 0x28000, v196
	global_store_dwordx4 v245, v[204:207], s[100:101]
	v_add_u32_e32 v244, 0x50000, v196
	global_load_dwordx4 v[188:191], v244, s[100:101]
	v_add_u32_e32 v245, 0x58000, v196
	global_load_dwordx4 v[192:195], v245, s[100:101]
	v_add_u32_e32 v244, 0x70000, v196
	global_load_dwordx4 v[200:203], v244, s[100:101]
	v_add_u32_e32 v245, 0x78000, v196
	global_load_dwordx4 v[204:207], v245, s[100:101]
	ds_read_b128 v[64:67], v197 offset:35840
	ds_read_b128 v[68:71], v197 offset:44288
	ds_read_b128 v[72:75], v197 offset:52736
	ds_read_b128 v[76:79], v197 offset:61184
	s_waitcnt lgkmcnt(3)
	v_lshlrev_b32_e32 v80, 16, v64
	v_and_b32_e32 v81, 0xffff0000, v64
	v_lshlrev_b32_e32 v82, 16, v65
	v_and_b32_e32 v83, 0xffff0000, v65
	v_lshlrev_b32_e32 v84, 16, v66
	v_and_b32_e32 v85, 0xffff0000, v66
	v_lshlrev_b32_e32 v86, 16, v67
	v_and_b32_e32 v87, 0xffff0000, v67
	s_waitcnt vmcnt(15)
	v_lshlrev_b32_e32 v88, 16, v208
	v_and_b32_e32 v89, 0xffff0000, v208
	v_lshlrev_b32_e32 v90, 16, v209
	v_and_b32_e32 v91, 0xffff0000, v209
	v_lshlrev_b32_e32 v92, 16, v210
	v_and_b32_e32 v93, 0xffff0000, v210
	v_lshlrev_b32_e32 v94, 16, v211
	v_and_b32_e32 v95, 0xffff0000, v211
	v_pk_mul_f32 v[88:89], v[88:89], v[80:81]
	v_pk_mul_f32 v[90:91], v[90:91], v[82:83]
	v_pk_mul_f32 v[92:93], v[92:93], v[84:85]
	v_pk_mul_f32 v[94:95], v[94:95], v[86:87]
	v_cvt_pk_bf16_f32 v208, v88, v89
	v_cvt_pk_bf16_f32 v209, v90, v91
	v_cvt_pk_bf16_f32 v210, v92, v93
	v_cvt_pk_bf16_f32 v211, v94, v95
	v_add_u32_e32 v244, 0x40000, v196
	global_store_dwordx4 v244, v[208:211], s[100:101]
	s_waitcnt lgkmcnt(2)
	v_lshlrev_b32_e32 v80, 16, v68
	v_and_b32_e32 v81, 0xffff0000, v68
	v_lshlrev_b32_e32 v82, 16, v69
	v_and_b32_e32 v83, 0xffff0000, v69
	v_lshlrev_b32_e32 v84, 16, v70
	v_and_b32_e32 v85, 0xffff0000, v70
	v_lshlrev_b32_e32 v86, 16, v71
	v_and_b32_e32 v87, 0xffff0000, v71
	s_waitcnt vmcnt(15)
	v_lshlrev_b32_e32 v88, 16, v212
	v_and_b32_e32 v89, 0xffff0000, v212
	v_lshlrev_b32_e32 v90, 16, v213
	v_and_b32_e32 v91, 0xffff0000, v213
	v_lshlrev_b32_e32 v92, 16, v214
	v_and_b32_e32 v93, 0xffff0000, v214
	v_lshlrev_b32_e32 v94, 16, v215
	v_and_b32_e32 v95, 0xffff0000, v215
	v_pk_mul_f32 v[88:89], v[88:89], v[80:81]
	v_pk_mul_f32 v[90:91], v[90:91], v[82:83]
	v_pk_mul_f32 v[92:93], v[92:93], v[84:85]
	v_pk_mul_f32 v[94:95], v[94:95], v[86:87]
	v_cvt_pk_bf16_f32 v212, v88, v89
	v_cvt_pk_bf16_f32 v213, v90, v91
	v_cvt_pk_bf16_f32 v214, v92, v93
	v_cvt_pk_bf16_f32 v215, v94, v95
	v_add_u32_e32 v245, 0x48000, v196
	global_store_dwordx4 v245, v[212:215], s[100:101]
	s_waitcnt lgkmcnt(1)
	v_lshlrev_b32_e32 v80, 16, v72
	v_and_b32_e32 v81, 0xffff0000, v72
	v_lshlrev_b32_e32 v82, 16, v73
	v_and_b32_e32 v83, 0xffff0000, v73
	v_lshlrev_b32_e32 v84, 16, v74
	v_and_b32_e32 v85, 0xffff0000, v74
	v_lshlrev_b32_e32 v86, 16, v75
	v_and_b32_e32 v87, 0xffff0000, v75
	s_waitcnt vmcnt(15)
	v_lshlrev_b32_e32 v88, 16, v216
	v_and_b32_e32 v89, 0xffff0000, v216
	v_lshlrev_b32_e32 v90, 16, v217
	v_and_b32_e32 v91, 0xffff0000, v217
	v_lshlrev_b32_e32 v92, 16, v218
	v_and_b32_e32 v93, 0xffff0000, v218
	v_lshlrev_b32_e32 v94, 16, v219
	v_and_b32_e32 v95, 0xffff0000, v219
	v_pk_mul_f32 v[88:89], v[88:89], v[80:81]
	v_pk_mul_f32 v[90:91], v[90:91], v[82:83]
	v_pk_mul_f32 v[92:93], v[92:93], v[84:85]
	v_pk_mul_f32 v[94:95], v[94:95], v[86:87]
	v_cvt_pk_bf16_f32 v216, v88, v89
	v_cvt_pk_bf16_f32 v217, v90, v91
	v_cvt_pk_bf16_f32 v218, v92, v93
	v_cvt_pk_bf16_f32 v219, v94, v95
	v_add_u32_e32 v244, 0x60000, v196
	global_store_dwordx4 v244, v[216:219], s[100:101]
	s_waitcnt lgkmcnt(0)
	v_lshlrev_b32_e32 v80, 16, v76
	v_and_b32_e32 v81, 0xffff0000, v76
	v_lshlrev_b32_e32 v82, 16, v77
	v_and_b32_e32 v83, 0xffff0000, v77
	v_lshlrev_b32_e32 v84, 16, v78
	v_and_b32_e32 v85, 0xffff0000, v78
	v_lshlrev_b32_e32 v86, 16, v79
	v_and_b32_e32 v87, 0xffff0000, v79
	s_waitcnt vmcnt(15)
; DI unsigned pk2(float lo, float hi) { f32x2 v = {lo, hi}; bf2_t b = __builtin_convertvector(v, bf2_t); return __builtin_bit_cast(unsigned, b); }
; DI u32x2 pk4(float a, float b, float c, float d) { u32x2 r; r.x = pk2(a, b); r.y = pk2(c, d); return r; }
; DI float bf_lo(unsigned u) { return __uint_as_float(u << 16); }
; DI float bf_hi(unsigned u) { return __uint_as_float(u & 0xffff0000u); }
; DI float fsilu(float z) { return z * fsigmoid(z); }
; template <int WI, int WGJ, class GetF, class LdF, class FinF>
; DI void staged_rows_rmw(unsigned char* lds, int tid, GetF get, LdF ld, FinF fin) {
;     ...
;     for (int jt = 0; jt < 2; ++jt) {
;         unsigned char* wrow = lds + (wj * 32 + ln) * RS + (wi * WI * 32 + 4 * h) * 2;
; #pragma unroll
;         for (int it = 0; it < WI; ++it)
; #pragma unroll
;             for (int g = 0; g < 4; ++g) *(u32x2*)(wrow + (it * 32 + 8 * g) * 2) = get(it, jt, g);
;         constexpr int NGRP = 2, GSZ = NIT / NGRP;
;         __syncthreads();
; #pragma unroll 1
;         for (int gq = 0; gq < NGRP; ++gq) {
;             decltype(ld(0, 0)) fetched[GSZ];
; #pragma unroll
;             for (int c = 0; c < GSZ; ++c) {
;                 const int idx = tid + (gq * GSZ + c) * NT, lr = idx / NCH, ch = idx % NCH;
;                 fetched[c] = ld((lr >> 5) * 64 + jt * 32 + (lr & 31), ch * 8);
;             }
; #pragma unroll
;             for (int c = 0; c < GSZ; ++c) {
;                 const int idx = tid + (gq * GSZ + c) * NT, lr = idx / NCH, ch = idx % NCH;
;                 const u32x4 v = *(const u32x4*)(lds + lr * RS + ch * 16);
;                 fin((lr >> 5) * 64 + jt * 32 + (lr & 31), ch * 8, v, fetched[c]);
; DI void phase3b(const Params& p, unsigned char* smem, int tid) {
;     ...
;                 [&](int it, int jt, int g) { const float sc = rsj[jt];
;                     return pk4(fsilu(acc[it][jt][4 * g] * sc), fsilu(acc[it][jt][4 * g + 1] * sc), fsilu(acc[it][jt][4 * g + 2] * sc), fsilu(acc[it][jt][4 * g + 3] * sc)); },
;                 [&](int row, int col) { return *(const u32x4*)(obuf + (size_t)(r0 + row) * 1024 + col); },
;                 [&](int row, int col, u32x4 v, u32x4 o) { u32x4 w;
; #pragma unroll
;                     for (int e = 0; e < 4; ++e) w[e] = pk2(bf_lo(o[e]) * bf_lo(v[e]), bf_hi(o[e]) * bf_hi(v[e]));
;                     *(u32x4*)(obuf + (size_t)(r0 + row) * 1024 + col) = w; });
	v_lshlrev_b32_e32 v88, 16, v220
	v_and_b32_e32 v89, 0xffff0000, v220
	v_lshlrev_b32_e32 v90, 16, v221
	v_and_b32_e32 v91, 0xffff0000, v221
	v_lshlrev_b32_e32 v92, 16, v222
	v_and_b32_e32 v93, 0xffff0000, v222
	v_lshlrev_b32_e32 v94, 16, v223
	v_and_b32_e32 v95, 0xffff0000, v223
	v_pk_mul_f32 v[88:89], v[88:89], v[80:81]
	v_pk_mul_f32 v[90:91], v[90:91], v[82:83]
	v_pk_mul_f32 v[92:93], v[92:93], v[84:85]
	v_pk_mul_f32 v[94:95], v[94:95], v[86:87]
	v_cvt_pk_bf16_f32 v220, v88, v89
	v_cvt_pk_bf16_f32 v221, v90, v91
	v_cvt_pk_bf16_f32 v222, v92, v93
	v_cvt_pk_bf16_f32 v223, v94, v95
	v_add_u32_e32 v245, 0x68000, v196
	global_store_dwordx4 v245, v[220:223], s[100:101]
	v_pk_mul_f32 v[48:49], v[48:49], v[176:177] op_sel_hi:[1,0]
	v_pk_mul_f32 v[50:51], v[50:51], v[176:177] op_sel_hi:[1,0]
	v_mul_f32_e32 v64, 0xbfb8aa3b, v48
	v_mul_f32_e32 v65, 0xbfb8aa3b, v49
	v_exp_f32_e32 v64, v64
	v_exp_f32_e32 v65, v65
	v_mul_f32_e32 v66, 0xbfb8aa3b, v50
	v_mul_f32_e32 v67, 0xbfb8aa3b, v51
	v_add_f32_e32 v64, 1.0, v64
	v_add_f32_e32 v65, 1.0, v65
	v_rcp_f32_e32 v64, v64
	v_rcp_f32_e32 v65, v65
	v_exp_f32_e32 v66, v66
	v_exp_f32_e32 v67, v67
	v_pk_mul_f32 v[52:53], v[52:53], v[176:177] op_sel_hi:[1,0]
	v_pk_mul_f32 v[48:49], v[48:49], v[64:65]
	v_add_f32_e32 v64, 1.0, v66
	v_add_f32_e32 v65, 1.0, v67
	v_mul_f32_e32 v66, 0xbfb8aa3b, v52
	v_mul_f32_e32 v67, 0xbfb8aa3b, v53
	v_rcp_f32_e32 v64, v64
	v_rcp_f32_e32 v65, v65
	v_exp_f32_e32 v66, v66
	v_exp_f32_e32 v67, v67
	v_pk_mul_f32 v[54:55], v[54:55], v[176:177] op_sel_hi:[1,0]
	v_pk_mul_f32 v[50:51], v[50:51], v[64:65]
	v_add_f32_e32 v64, 1.0, v66
	v_add_f32_e32 v65, 1.0, v67
	v_mul_f32_e32 v66, 0xbfb8aa3b, v54
	v_mul_f32_e32 v67, 0xbfb8aa3b, v55
	v_exp_f32_e32 v66, v66
	v_exp_f32_e32 v67, v67
	v_rcp_f32_e32 v64, v64
	v_rcp_f32_e32 v65, v65
	v_add_f32_e32 v66, 1.0, v66
	v_add_f32_e32 v67, 1.0, v67
	v_rcp_f32_e32 v66, v66
	v_rcp_f32_e32 v67, v67
	v_cvt_pk_bf16_f32 v48, v48, v49
	v_cvt_pk_bf16_f32 v49, v50, v51
	v_pk_mul_f32 v[50:51], v[52:53], v[64:65]
	v_pk_mul_f32 v[52:53], v[54:55], v[66:67]
	v_cvt_pk_bf16_f32 v50, v50, v51
	v_cvt_pk_bf16_f32 v51, v52, v53
	v_pk_mul_f32 v[52:53], v[56:57], v[176:177] op_sel_hi:[1,0]
	s_nop 0
	v_mul_f32_e32 v54, 0xbfb8aa3b, v52
	v_mul_f32_e32 v55, 0xbfb8aa3b, v53
	v_exp_f32_e32 v54, v54
	v_exp_f32_e32 v55, v55
	s_barrier
	ds_write2_b64 v112, v[48:49], v[50:51] offset1:2
	v_pk_mul_f32 v[50:51], v[58:59], v[176:177] op_sel_hi:[1,0]
	v_add_f32_e32 v48, 1.0, v54
	v_add_f32_e32 v49, 1.0, v55
	v_mul_f32_e32 v54, 0xbfb8aa3b, v50
	v_mul_f32_e32 v55, 0xbfb8aa3b, v51
	v_rcp_f32_e32 v48, v48
	v_rcp_f32_e32 v49, v49
	v_exp_f32_e32 v54, v54
	v_exp_f32_e32 v55, v55
	v_pk_mul_f32 v[32:33], v[32:33], v[176:177] op_sel_hi:[1,0]
	v_pk_mul_f32 v[48:49], v[52:53], v[48:49]
	v_add_f32_e32 v52, 1.0, v54
	v_add_f32_e32 v53, 1.0, v55
	v_pk_mul_f32 v[54:55], v[60:61], v[176:177] op_sel_hi:[1,0]
	v_rcp_f32_e32 v52, v52
	v_mul_f32_e32 v56, 0xbfb8aa3b, v54
	v_mul_f32_e32 v57, 0xbfb8aa3b, v55
	v_rcp_f32_e32 v53, v53
	v_exp_f32_e32 v56, v56
	v_exp_f32_e32 v57, v57
	v_cvt_pk_bf16_f32 v48, v48, v49
	v_pk_mul_f32 v[50:51], v[50:51], v[52:53]
	v_add_f32_e32 v52, 1.0, v56
	v_add_f32_e32 v53, 1.0, v57
	v_pk_mul_f32 v[56:57], v[62:63], v[176:177] op_sel_hi:[1,0]
	v_rcp_f32_e32 v52, v52
	v_mul_f32_e32 v58, 0xbfb8aa3b, v56
	v_mul_f32_e32 v59, 0xbfb8aa3b, v57
	v_exp_f32_e32 v58, v58
	v_exp_f32_e32 v59, v59
	v_rcp_f32_e32 v53, v53
	v_cvt_pk_bf16_f32 v49, v50, v51
	v_add_f32_e32 v58, 1.0, v58
	v_add_f32_e32 v59, 1.0, v59
	v_rcp_f32_e32 v58, v58
	v_rcp_f32_e32 v59, v59
	v_pk_mul_f32 v[50:51], v[54:55], v[52:53]
	v_pk_mul_f32 v[34:35], v[34:35], v[176:177] op_sel_hi:[1,0]
	v_cvt_pk_bf16_f32 v50, v50, v51
	v_pk_mul_f32 v[52:53], v[56:57], v[58:59]
	v_pk_mul_f32 v[36:37], v[36:37], v[176:177] op_sel_hi:[1,0]
	v_cvt_pk_bf16_f32 v51, v52, v53
	v_mul_f32_e32 v52, 0xbfb8aa3b, v32
	v_mul_f32_e32 v53, 0xbfb8aa3b, v33
	v_exp_f32_e32 v52, v52
	v_exp_f32_e32 v53, v53
	ds_write2_b64 v112, v[48:49], v[50:51] offset0:4 offset1:6
	v_mul_f32_e32 v50, 0xbfb8aa3b, v34
	v_add_f32_e32 v48, 1.0, v52
	v_add_f32_e32 v49, 1.0, v53
	v_mul_f32_e32 v51, 0xbfb8aa3b, v35
	v_rcp_f32_e32 v48, v48
	v_rcp_f32_e32 v49, v49
	v_exp_f32_e32 v50, v50
	v_exp_f32_e32 v51, v51
	v_pk_mul_f32 v[38:39], v[38:39], v[176:177] op_sel_hi:[1,0]
	v_pk_mul_f32 v[32:33], v[32:33], v[48:49]
	v_add_f32_e32 v48, 1.0, v50
	v_add_f32_e32 v49, 1.0, v51
	v_mul_f32_e32 v50, 0xbfb8aa3b, v36
	v_mul_f32_e32 v51, 0xbfb8aa3b, v37
	v_rcp_f32_e32 v48, v48
	v_rcp_f32_e32 v49, v49
	v_exp_f32_e32 v50, v50
	v_exp_f32_e32 v51, v51
	v_cvt_pk_bf16_f32 v32, v32, v33
	v_pk_mul_f32 v[34:35], v[34:35], v[48:49]
	v_add_f32_e32 v48, 1.0, v50
	v_add_f32_e32 v49, 1.0, v51
	v_mul_f32_e32 v50, 0xbfb8aa3b, v38
	v_mul_f32_e32 v51, 0xbfb8aa3b, v39
	v_exp_f32_e32 v50, v50
	v_exp_f32_e32 v51, v51
	v_rcp_f32_e32 v48, v48
	v_rcp_f32_e32 v49, v49
	v_add_f32_e32 v50, 1.0, v50
	v_add_f32_e32 v51, 1.0, v51
	v_rcp_f32_e32 v50, v50
	v_rcp_f32_e32 v51, v51
	v_cvt_pk_bf16_f32 v33, v34, v35
	v_pk_mul_f32 v[34:35], v[36:37], v[48:49]
	v_pk_mul_f32 v[16:17], v[16:17], v[176:177] op_sel_hi:[1,0]
	v_pk_mul_f32 v[36:37], v[38:39], v[50:51]
	v_cvt_pk_bf16_f32 v34, v34, v35
	v_cvt_pk_bf16_f32 v35, v36, v37
	v_pk_mul_f32 v[36:37], v[40:41], v[176:177] op_sel_hi:[1,0]
	ds_write2_b64 v112, v[32:33], v[34:35] offset0:8 offset1:10
	v_mul_f32_e32 v38, 0xbfb8aa3b, v36
	v_mul_f32_e32 v39, 0xbfb8aa3b, v37
	v_exp_f32_e32 v38, v38
	v_exp_f32_e32 v39, v39
	v_pk_mul_f32 v[34:35], v[42:43], v[176:177] op_sel_hi:[1,0]
	v_pk_mul_f32 v[18:19], v[18:19], v[176:177] op_sel_hi:[1,0]
	v_add_f32_e32 v32, 1.0, v38
	v_add_f32_e32 v33, 1.0, v39
; DI u32x2 pk4(float a, float b, float c, float d) { u32x2 r; r.x = pk2(a, b); r.y = pk2(c, d); return r; }
; DI float fsilu(float z) { return z * fsigmoid(z); }
; template <int WI, int WGJ, class GetF, class LdF, class FinF>
; DI void staged_rows_rmw(unsigned char* lds, int tid, GetF get, LdF ld, FinF fin) {
;     ...
;         for (int it = 0; it < WI; ++it)
; #pragma unroll
;             for (int g = 0; g < 4; ++g) *(u32x2*)(wrow + (it * 32 + 8 * g) * 2) = get(it, jt, g);
; DI void phase3b(const Params& p, unsigned char* smem, int tid) {
;     ...
;                 [&](int it, int jt, int g) { const float sc = rsj[jt];
;                     return pk4(fsilu(acc[it][jt][4 * g] * sc), fsilu(acc[it][jt][4 * g + 1] * sc), fsilu(acc[it][jt][4 * g + 2] * sc), fsilu(acc[it][jt][4 * g + 3] * sc)); },
	v_mul_f32_e32 v38, 0xbfb8aa3b, v34
	v_mul_f32_e32 v39, 0xbfb8aa3b, v35
	v_rcp_f32_e32 v32, v32
	v_rcp_f32_e32 v33, v33
	v_exp_f32_e32 v38, v38
	v_exp_f32_e32 v39, v39
	v_pk_mul_f32 v[20:21], v[20:21], v[176:177] op_sel_hi:[1,0]
	v_pk_mul_f32 v[32:33], v[36:37], v[32:33]
	v_add_f32_e32 v36, 1.0, v38
	v_add_f32_e32 v37, 1.0, v39
	v_pk_mul_f32 v[38:39], v[44:45], v[176:177] op_sel_hi:[1,0]
	v_rcp_f32_e32 v36, v36
	v_mul_f32_e32 v40, 0xbfb8aa3b, v38
	v_mul_f32_e32 v41, 0xbfb8aa3b, v39
	v_rcp_f32_e32 v37, v37
	v_exp_f32_e32 v40, v40
	v_exp_f32_e32 v41, v41
	v_cvt_pk_bf16_f32 v32, v32, v33
	v_pk_mul_f32 v[34:35], v[34:35], v[36:37]
	v_add_f32_e32 v36, 1.0, v40
	v_add_f32_e32 v37, 1.0, v41
	v_pk_mul_f32 v[40:41], v[46:47], v[176:177] op_sel_hi:[1,0]
	v_rcp_f32_e32 v36, v36
	v_mul_f32_e32 v42, 0xbfb8aa3b, v40
	v_mul_f32_e32 v43, 0xbfb8aa3b, v41
	v_exp_f32_e32 v42, v42
	v_exp_f32_e32 v43, v43
	v_rcp_f32_e32 v37, v37
	v_cvt_pk_bf16_f32 v33, v34, v35
	v_add_f32_e32 v42, 1.0, v42
	v_add_f32_e32 v43, 1.0, v43
	v_rcp_f32_e32 v42, v42
	v_rcp_f32_e32 v43, v43
	v_pk_mul_f32 v[34:35], v[38:39], v[36:37]
	v_pk_mul_f32 v[22:23], v[22:23], v[176:177] op_sel_hi:[1,0]
	v_cvt_pk_bf16_f32 v34, v34, v35
	v_pk_mul_f32 v[36:37], v[40:41], v[42:43]
	v_pk_mul_f32 v[0:1], v[0:1], v[176:177] op_sel_hi:[1,0]
	v_cvt_pk_bf16_f32 v35, v36, v37
	v_mul_f32_e32 v36, 0xbfb8aa3b, v16
	v_mul_f32_e32 v37, 0xbfb8aa3b, v17
	v_exp_f32_e32 v36, v36
	v_exp_f32_e32 v37, v37
	ds_write2_b64 v112, v[32:33], v[34:35] offset0:12 offset1:14
	v_mul_f32_e32 v34, 0xbfb8aa3b, v18
	v_add_f32_e32 v32, 1.0, v36
	v_add_f32_e32 v33, 1.0, v37
	v_mul_f32_e32 v35, 0xbfb8aa3b, v19
	v_rcp_f32_e32 v32, v32
	v_rcp_f32_e32 v33, v33
	v_exp_f32_e32 v34, v34
	v_exp_f32_e32 v35, v35
	v_pk_mul_f32 v[2:3], v[2:3], v[176:177] op_sel_hi:[1,0]
	v_pk_mul_f32 v[16:17], v[16:17], v[32:33]
	v_add_f32_e32 v32, 1.0, v34
	v_add_f32_e32 v33, 1.0, v35
	v_mul_f32_e32 v34, 0xbfb8aa3b, v20
	v_mul_f32_e32 v35, 0xbfb8aa3b, v21
	v_rcp_f32_e32 v32, v32
	v_rcp_f32_e32 v33, v33
	v_exp_f32_e32 v34, v34
	v_exp_f32_e32 v35, v35
	v_cvt_pk_bf16_f32 v16, v16, v17
	v_pk_mul_f32 v[18:19], v[18:19], v[32:33]
	v_add_f32_e32 v32, 1.0, v34
	v_add_f32_e32 v33, 1.0, v35
	v_mul_f32_e32 v34, 0xbfb8aa3b, v22
	v_mul_f32_e32 v35, 0xbfb8aa3b, v23
	v_exp_f32_e32 v34, v34
	v_exp_f32_e32 v35, v35
	v_rcp_f32_e32 v32, v32
	v_rcp_f32_e32 v33, v33
	v_add_f32_e32 v34, 1.0, v34
	v_add_f32_e32 v35, 1.0, v35
	v_rcp_f32_e32 v34, v34
	v_rcp_f32_e32 v35, v35
	v_cvt_pk_bf16_f32 v17, v18, v19
	v_pk_mul_f32 v[18:19], v[20:21], v[32:33]
	v_pk_mul_f32 v[4:5], v[4:5], v[176:177] op_sel_hi:[1,0]
	v_pk_mul_f32 v[20:21], v[22:23], v[34:35]
	v_cvt_pk_bf16_f32 v18, v18, v19
	v_cvt_pk_bf16_f32 v19, v20, v21
	v_pk_mul_f32 v[20:21], v[24:25], v[176:177] op_sel_hi:[1,0]
	ds_write2_b64 v112, v[16:17], v[18:19] offset0:16 offset1:18
	v_mul_f32_e32 v22, 0xbfb8aa3b, v20
	v_mul_f32_e32 v23, 0xbfb8aa3b, v21
	v_exp_f32_e32 v22, v22
	v_exp_f32_e32 v23, v23
	v_pk_mul_f32 v[18:19], v[26:27], v[176:177] op_sel_hi:[1,0]
	v_pk_mul_f32 v[6:7], v[6:7], v[176:177] op_sel_hi:[1,0]
	v_add_f32_e32 v16, 1.0, v22
	v_add_f32_e32 v17, 1.0, v23
	v_mul_f32_e32 v22, 0xbfb8aa3b, v18
	v_mul_f32_e32 v23, 0xbfb8aa3b, v19
	v_rcp_f32_e32 v16, v16
	v_rcp_f32_e32 v17, v17
	v_exp_f32_e32 v22, v22
	v_exp_f32_e32 v23, v23
	s_add_i32 s26, s26, 32
	v_pk_mul_f32 v[16:17], v[20:21], v[16:17]
	v_add_f32_e32 v20, 1.0, v22
	v_add_f32_e32 v21, 1.0, v23
	v_pk_mul_f32 v[22:23], v[28:29], v[176:177] op_sel_hi:[1,0]
	v_rcp_f32_e32 v20, v20
	v_mul_f32_e32 v24, 0xbfb8aa3b, v22
	v_mul_f32_e32 v25, 0xbfb8aa3b, v23
	v_rcp_f32_e32 v21, v21
	v_exp_f32_e32 v24, v24
	v_exp_f32_e32 v25, v25
	v_cvt_pk_bf16_f32 v16, v16, v17
	v_pk_mul_f32 v[18:19], v[18:19], v[20:21]
	v_add_f32_e32 v20, 1.0, v24
	v_add_f32_e32 v21, 1.0, v25
	v_pk_mul_f32 v[24:25], v[30:31], v[176:177] op_sel_hi:[1,0]
	v_rcp_f32_e32 v20, v20
	v_mul_f32_e32 v26, 0xbfb8aa3b, v24
	v_mul_f32_e32 v27, 0xbfb8aa3b, v25
	v_exp_f32_e32 v26, v26
	v_exp_f32_e32 v27, v27
	v_rcp_f32_e32 v21, v21
	v_cvt_pk_bf16_f32 v17, v18, v19
	v_add_f32_e32 v26, 1.0, v26
	v_add_f32_e32 v27, 1.0, v27
	v_rcp_f32_e32 v26, v26
	v_rcp_f32_e32 v27, v27
	v_pk_mul_f32 v[18:19], v[22:23], v[20:21]
	s_mov_b32 s14, 0
	v_cvt_pk_bf16_f32 v18, v18, v19
	v_pk_mul_f32 v[20:21], v[24:25], v[26:27]
	s_mov_b64 s[24:25], -1
	v_cvt_pk_bf16_f32 v19, v20, v21
	v_mul_f32_e32 v20, 0xbfb8aa3b, v0
	v_mul_f32_e32 v21, 0xbfb8aa3b, v1
	v_exp_f32_e32 v20, v20
	v_exp_f32_e32 v21, v21
	ds_write2_b64 v112, v[16:17], v[18:19] offset0:20 offset1:22
	v_mul_f32_e32 v18, 0xbfb8aa3b, v2
	v_add_f32_e32 v16, 1.0, v20
	v_add_f32_e32 v17, 1.0, v21
	v_mul_f32_e32 v19, 0xbfb8aa3b, v3
	v_rcp_f32_e32 v16, v16
	v_rcp_f32_e32 v17, v17
	v_exp_f32_e32 v18, v18
	v_exp_f32_e32 v19, v19
	v_pk_mul_f32 v[0:1], v[0:1], v[16:17]
	v_add_f32_e32 v16, 1.0, v18
	v_add_f32_e32 v17, 1.0, v19
	v_mul_f32_e32 v18, 0xbfb8aa3b, v4
	v_mul_f32_e32 v19, 0xbfb8aa3b, v5
	v_rcp_f32_e32 v16, v16
	v_rcp_f32_e32 v17, v17
	v_exp_f32_e32 v18, v18
	v_exp_f32_e32 v19, v19
	v_cvt_pk_bf16_f32 v0, v0, v1
	v_pk_mul_f32 v[2:3], v[2:3], v[16:17]
	v_add_f32_e32 v16, 1.0, v18
	v_add_f32_e32 v17, 1.0, v19
	v_mul_f32_e32 v18, 0xbfb8aa3b, v6
	v_mul_f32_e32 v19, 0xbfb8aa3b, v7
	v_exp_f32_e32 v18, v18
	v_exp_f32_e32 v19, v19
	v_rcp_f32_e32 v16, v16
	v_rcp_f32_e32 v17, v17
	v_add_f32_e32 v18, 1.0, v18
	v_add_f32_e32 v19, 1.0, v19
	v_rcp_f32_e32 v18, v18
	v_rcp_f32_e32 v19, v19
	v_cvt_pk_bf16_f32 v1, v2, v3
	v_pk_mul_f32 v[2:3], v[4:5], v[16:17]
	v_pk_mul_f32 v[4:5], v[6:7], v[18:19]
	v_cvt_pk_bf16_f32 v2, v2, v3
	v_cvt_pk_bf16_f32 v3, v4, v5
	v_pk_mul_f32 v[4:5], v[8:9], v[176:177] op_sel_hi:[1,0]
; DI unsigned pk2(float lo, float hi) { f32x2 v = {lo, hi}; bf2_t b = __builtin_convertvector(v, bf2_t); return __builtin_bit_cast(unsigned, b); }
; DI u32x2 pk4(float a, float b, float c, float d) { u32x2 r; r.x = pk2(a, b); r.y = pk2(c, d); return r; }
; DI float bf_lo(unsigned u) { return __uint_as_float(u << 16); }
; DI float bf_hi(unsigned u) { return __uint_as_float(u & 0xffff0000u); }
; DI float fsilu(float z) { return z * fsigmoid(z); }
; template <int WI, int WGJ, class GetF, class LdF, class FinF>
; DI void staged_rows_rmw(unsigned char* lds, int tid, GetF get, LdF ld, FinF fin) {
;     ...
;         for (int it = 0; it < WI; ++it)
; #pragma unroll
;             for (int g = 0; g < 4; ++g) *(u32x2*)(wrow + (it * 32 + 8 * g) * 2) = get(it, jt, g);
;         constexpr int NGRP = 2, GSZ = NIT / NGRP;
;         __syncthreads();
; #pragma unroll 1
;         for (int gq = 0; gq < NGRP; ++gq) {
;             decltype(ld(0, 0)) fetched[GSZ];
; #pragma unroll
;             for (int c = 0; c < GSZ; ++c) {
;                 const int idx = tid + (gq * GSZ + c) * NT, lr = idx / NCH, ch = idx % NCH;
;                 fetched[c] = ld((lr >> 5) * 64 + jt * 32 + (lr & 31), ch * 8);
;             }
; #pragma unroll
;             for (int c = 0; c < GSZ; ++c) {
;                 const int idx = tid + (gq * GSZ + c) * NT, lr = idx / NCH, ch = idx % NCH;
;                 const u32x4 v = *(const u32x4*)(lds + lr * RS + ch * 16);
;                 fin((lr >> 5) * 64 + jt * 32 + (lr & 31), ch * 8, v, fetched[c]);
; DI void phase3b(const Params& p, unsigned char* smem, int tid) {
;     ...
;                 [&](int it, int jt, int g) { const float sc = rsj[jt];
;                     return pk4(fsilu(acc[it][jt][4 * g] * sc), fsilu(acc[it][jt][4 * g + 1] * sc), fsilu(acc[it][jt][4 * g + 2] * sc), fsilu(acc[it][jt][4 * g + 3] * sc)); },
;                 [&](int row, int col) { return *(const u32x4*)(obuf + (size_t)(r0 + row) * 1024 + col); },
;                 [&](int row, int col, u32x4 v, u32x4 o) { u32x4 w;
; #pragma unroll
;                     for (int e = 0; e < 4; ++e) w[e] = pk2(bf_lo(o[e]) * bf_lo(v[e]), bf_hi(o[e]) * bf_hi(v[e]));
;                     *(u32x4*)(obuf + (size_t)(r0 + row) * 1024 + col) = w; });
	ds_write2_b64 v112, v[0:1], v[2:3] offset0:24 offset1:26
	v_mul_f32_e32 v6, 0xbfb8aa3b, v4
	v_mul_f32_e32 v7, 0xbfb8aa3b, v5
	v_exp_f32_e32 v6, v6
	v_exp_f32_e32 v7, v7
	v_pk_mul_f32 v[2:3], v[10:11], v[176:177] op_sel_hi:[1,0]
	v_add_f32_e32 v0, 1.0, v6
	v_add_f32_e32 v1, 1.0, v7
	v_mul_f32_e32 v6, 0xbfb8aa3b, v2
	v_mul_f32_e32 v7, 0xbfb8aa3b, v3
	v_rcp_f32_e32 v0, v0
	v_rcp_f32_e32 v1, v1
	v_exp_f32_e32 v6, v6
	v_exp_f32_e32 v7, v7
	v_pk_mul_f32 v[0:1], v[4:5], v[0:1]
	v_add_f32_e32 v4, 1.0, v6
	v_add_f32_e32 v5, 1.0, v7
	v_pk_mul_f32 v[6:7], v[12:13], v[176:177] op_sel_hi:[1,0]
	v_rcp_f32_e32 v4, v4
	v_mul_f32_e32 v8, 0xbfb8aa3b, v6
	v_mul_f32_e32 v9, 0xbfb8aa3b, v7
	v_rcp_f32_e32 v5, v5
	v_exp_f32_e32 v8, v8
	v_exp_f32_e32 v9, v9
	v_cvt_pk_bf16_f32 v0, v0, v1
	v_pk_mul_f32 v[2:3], v[2:3], v[4:5]
	v_add_f32_e32 v4, 1.0, v8
	v_add_f32_e32 v5, 1.0, v9
	v_pk_mul_f32 v[8:9], v[14:15], v[176:177] op_sel_hi:[1,0]
	v_rcp_f32_e32 v4, v4
	v_mul_f32_e32 v10, 0xbfb8aa3b, v8
	v_mul_f32_e32 v11, 0xbfb8aa3b, v9
	v_exp_f32_e32 v10, v10
	v_exp_f32_e32 v11, v11
	v_rcp_f32_e32 v5, v5
	v_cvt_pk_bf16_f32 v1, v2, v3
	v_add_f32_e32 v10, 1.0, v10
	v_add_f32_e32 v11, 1.0, v11
	v_rcp_f32_e32 v10, v10
	v_rcp_f32_e32 v11, v11
	v_pk_mul_f32 v[2:3], v[6:7], v[4:5]
	v_pk_mul_f32 v[4:5], v[8:9], v[10:11]
	v_cvt_pk_bf16_f32 v2, v2, v3
	v_cvt_pk_bf16_f32 v3, v4, v5
	ds_write2_b64 v112, v[0:1], v[2:3] offset0:28 offset1:30
	s_waitcnt lgkmcnt(0)
	s_barrier
	ds_read_b128 v[64:67], v197 offset:2048
	ds_read_b128 v[68:71], v197 offset:10496
	ds_read_b128 v[72:75], v197 offset:18944
	ds_read_b128 v[76:79], v197 offset:27392
	s_waitcnt lgkmcnt(3)
	v_lshlrev_b32_e32 v80, 16, v64
	v_and_b32_e32 v81, 0xffff0000, v64
	v_lshlrev_b32_e32 v82, 16, v65
	v_and_b32_e32 v83, 0xffff0000, v65
	v_lshlrev_b32_e32 v84, 16, v66
	v_and_b32_e32 v85, 0xffff0000, v66
	v_lshlrev_b32_e32 v86, 16, v67
	v_and_b32_e32 v87, 0xffff0000, v67
	s_waitcnt vmcnt(15)
	v_lshlrev_b32_e32 v88, 16, v224
	v_and_b32_e32 v89, 0xffff0000, v224
	v_lshlrev_b32_e32 v90, 16, v225
	v_and_b32_e32 v91, 0xffff0000, v225
	v_lshlrev_b32_e32 v92, 16, v226
	v_and_b32_e32 v93, 0xffff0000, v226
	v_lshlrev_b32_e32 v94, 16, v227
	v_and_b32_e32 v95, 0xffff0000, v227
	v_pk_mul_f32 v[88:89], v[88:89], v[80:81]
	v_pk_mul_f32 v[90:91], v[90:91], v[82:83]
	v_pk_mul_f32 v[92:93], v[92:93], v[84:85]
	v_pk_mul_f32 v[94:95], v[94:95], v[86:87]
	v_cvt_pk_bf16_f32 v224, v88, v89
	v_cvt_pk_bf16_f32 v225, v90, v91
	v_cvt_pk_bf16_f32 v226, v92, v93
	v_cvt_pk_bf16_f32 v227, v94, v95
	v_add_u32_e32 v244, 0x10000, v196
	global_store_dwordx4 v244, v[224:227], s[100:101]
	s_waitcnt lgkmcnt(2)
	v_lshlrev_b32_e32 v80, 16, v68
	v_and_b32_e32 v81, 0xffff0000, v68
	v_lshlrev_b32_e32 v82, 16, v69
	v_and_b32_e32 v83, 0xffff0000, v69
	v_lshlrev_b32_e32 v84, 16, v70
	v_and_b32_e32 v85, 0xffff0000, v70
	v_lshlrev_b32_e32 v86, 16, v71
	v_and_b32_e32 v87, 0xffff0000, v71
	s_waitcnt vmcnt(15)
	v_lshlrev_b32_e32 v88, 16, v228
	v_and_b32_e32 v89, 0xffff0000, v228
	v_lshlrev_b32_e32 v90, 16, v229
	v_and_b32_e32 v91, 0xffff0000, v229
	v_lshlrev_b32_e32 v92, 16, v230
	v_and_b32_e32 v93, 0xffff0000, v230
	v_lshlrev_b32_e32 v94, 16, v231
	v_and_b32_e32 v95, 0xffff0000, v231
	v_pk_mul_f32 v[88:89], v[88:89], v[80:81]
	v_pk_mul_f32 v[90:91], v[90:91], v[82:83]
	v_pk_mul_f32 v[92:93], v[92:93], v[84:85]
	v_pk_mul_f32 v[94:95], v[94:95], v[86:87]
	v_cvt_pk_bf16_f32 v228, v88, v89
	v_cvt_pk_bf16_f32 v229, v90, v91
	v_cvt_pk_bf16_f32 v230, v92, v93
	v_cvt_pk_bf16_f32 v231, v94, v95
	v_add_u32_e32 v245, 0x18000, v196
	global_store_dwordx4 v245, v[228:231], s[100:101]
	s_waitcnt lgkmcnt(1)
	v_lshlrev_b32_e32 v80, 16, v72
	v_and_b32_e32 v81, 0xffff0000, v72
	v_lshlrev_b32_e32 v82, 16, v73
	v_and_b32_e32 v83, 0xffff0000, v73
	v_lshlrev_b32_e32 v84, 16, v74
	v_and_b32_e32 v85, 0xffff0000, v74
	v_lshlrev_b32_e32 v86, 16, v75
	v_and_b32_e32 v87, 0xffff0000, v75
	s_waitcnt vmcnt(15)
	v_lshlrev_b32_e32 v88, 16, v232
	v_and_b32_e32 v89, 0xffff0000, v232
	v_lshlrev_b32_e32 v90, 16, v233
	v_and_b32_e32 v91, 0xffff0000, v233
	v_lshlrev_b32_e32 v92, 16, v234
	v_and_b32_e32 v93, 0xffff0000, v234
	v_lshlrev_b32_e32 v94, 16, v235
	v_and_b32_e32 v95, 0xffff0000, v235
	v_pk_mul_f32 v[88:89], v[88:89], v[80:81]
	v_pk_mul_f32 v[90:91], v[90:91], v[82:83]
	v_pk_mul_f32 v[92:93], v[92:93], v[84:85]
	v_pk_mul_f32 v[94:95], v[94:95], v[86:87]
	v_cvt_pk_bf16_f32 v232, v88, v89
	v_cvt_pk_bf16_f32 v233, v90, v91
	v_cvt_pk_bf16_f32 v234, v92, v93
	v_cvt_pk_bf16_f32 v235, v94, v95
	v_add_u32_e32 v244, 0x30000, v196
	global_store_dwordx4 v244, v[232:235], s[100:101]
	s_waitcnt lgkmcnt(0)
	v_lshlrev_b32_e32 v80, 16, v76
	v_and_b32_e32 v81, 0xffff0000, v76
	v_lshlrev_b32_e32 v82, 16, v77
	v_and_b32_e32 v83, 0xffff0000, v77
	v_lshlrev_b32_e32 v84, 16, v78
	v_and_b32_e32 v85, 0xffff0000, v78
	v_lshlrev_b32_e32 v86, 16, v79
	v_and_b32_e32 v87, 0xffff0000, v79
	s_waitcnt vmcnt(15)
; DI unsigned pk2(float lo, float hi) { f32x2 v = {lo, hi}; bf2_t b = __builtin_convertvector(v, bf2_t); return __builtin_bit_cast(unsigned, b); }
; DI float bf_lo(unsigned u) { return __uint_as_float(u << 16); }
; DI float bf_hi(unsigned u) { return __uint_as_float(u & 0xffff0000u); }
; template <int WI, int WGJ, class GetF, class LdF, class FinF>
; DI void staged_rows_rmw(unsigned char* lds, int tid, GetF get, LdF ld, FinF fin) {
;     ...
;             for (int c = 0; c < GSZ; ++c) {
;                 const int idx = tid + (gq * GSZ + c) * NT, lr = idx / NCH, ch = idx % NCH;
;                 const u32x4 v = *(const u32x4*)(lds + lr * RS + ch * 16);
;                 fin((lr >> 5) * 64 + jt * 32 + (lr & 31), ch * 8, v, fetched[c]);
;             }
;         }
;         __syncthreads();
;     }
; DI void phase3b(const Params& p, unsigned char* smem, int tid) {
;     ...
;                 [&](int row, int col) { return *(const u32x4*)(obuf + (size_t)(r0 + row) * 1024 + col); },
;                 [&](int row, int col, u32x4 v, u32x4 o) { u32x4 w;
; #pragma unroll
;                     for (int e = 0; e < 4; ++e) w[e] = pk2(bf_lo(o[e]) * bf_lo(v[e]), bf_hi(o[e]) * bf_hi(v[e]));
;                     *(u32x4*)(obuf + (size_t)(r0 + row) * 1024 + col) = w; });
	v_lshlrev_b32_e32 v88, 16, v236
	v_and_b32_e32 v89, 0xffff0000, v236
	v_lshlrev_b32_e32 v90, 16, v237
	v_and_b32_e32 v91, 0xffff0000, v237
	v_lshlrev_b32_e32 v92, 16, v238
	v_and_b32_e32 v93, 0xffff0000, v238
	v_lshlrev_b32_e32 v94, 16, v239
	v_and_b32_e32 v95, 0xffff0000, v239
	v_pk_mul_f32 v[88:89], v[88:89], v[80:81]
	v_pk_mul_f32 v[90:91], v[90:91], v[82:83]
	v_pk_mul_f32 v[92:93], v[92:93], v[84:85]
	v_pk_mul_f32 v[94:95], v[94:95], v[86:87]
	v_cvt_pk_bf16_f32 v236, v88, v89
	v_cvt_pk_bf16_f32 v237, v90, v91
	v_cvt_pk_bf16_f32 v238, v92, v93
	v_cvt_pk_bf16_f32 v239, v94, v95
	v_add_u32_e32 v245, 0x38000, v196
	global_store_dwordx4 v245, v[236:239], s[100:101]
	ds_read_b128 v[64:67], v197 offset:35840
	ds_read_b128 v[68:71], v197 offset:44288
	ds_read_b128 v[72:75], v197 offset:52736
	ds_read_b128 v[76:79], v197 offset:61184
	s_waitcnt lgkmcnt(3)
	v_lshlrev_b32_e32 v80, 16, v64
	v_and_b32_e32 v81, 0xffff0000, v64
	v_lshlrev_b32_e32 v82, 16, v65
	v_and_b32_e32 v83, 0xffff0000, v65
	v_lshlrev_b32_e32 v84, 16, v66
	v_and_b32_e32 v85, 0xffff0000, v66
	v_lshlrev_b32_e32 v86, 16, v67
	v_and_b32_e32 v87, 0xffff0000, v67
	s_waitcnt vmcnt(11)
	v_lshlrev_b32_e32 v88, 16, v188
	v_and_b32_e32 v89, 0xffff0000, v188
	v_lshlrev_b32_e32 v90, 16, v189
	v_and_b32_e32 v91, 0xffff0000, v189
	v_lshlrev_b32_e32 v92, 16, v190
	v_and_b32_e32 v93, 0xffff0000, v190
	v_lshlrev_b32_e32 v94, 16, v191
	v_and_b32_e32 v95, 0xffff0000, v191
	v_pk_mul_f32 v[88:89], v[88:89], v[80:81]
	v_pk_mul_f32 v[90:91], v[90:91], v[82:83]
	v_pk_mul_f32 v[92:93], v[92:93], v[84:85]
	v_pk_mul_f32 v[94:95], v[94:95], v[86:87]
	v_cvt_pk_bf16_f32 v188, v88, v89
	v_cvt_pk_bf16_f32 v189, v90, v91
	v_cvt_pk_bf16_f32 v190, v92, v93
	v_cvt_pk_bf16_f32 v191, v94, v95
	v_add_u32_e32 v244, 0x50000, v196
	global_store_dwordx4 v244, v[188:191], s[100:101]
	s_waitcnt lgkmcnt(2)
	v_lshlrev_b32_e32 v80, 16, v68
	v_and_b32_e32 v81, 0xffff0000, v68
	v_lshlrev_b32_e32 v82, 16, v69
	v_and_b32_e32 v83, 0xffff0000, v69
	v_lshlrev_b32_e32 v84, 16, v70
	v_and_b32_e32 v85, 0xffff0000, v70
	v_lshlrev_b32_e32 v86, 16, v71
	v_and_b32_e32 v87, 0xffff0000, v71
	s_waitcnt vmcnt(11)
	v_lshlrev_b32_e32 v88, 16, v192
	v_and_b32_e32 v89, 0xffff0000, v192
	v_lshlrev_b32_e32 v90, 16, v193
	v_and_b32_e32 v91, 0xffff0000, v193
	v_lshlrev_b32_e32 v92, 16, v194
	v_and_b32_e32 v93, 0xffff0000, v194
	v_lshlrev_b32_e32 v94, 16, v195
	v_and_b32_e32 v95, 0xffff0000, v195
	v_pk_mul_f32 v[88:89], v[88:89], v[80:81]
	v_pk_mul_f32 v[90:91], v[90:91], v[82:83]
	v_pk_mul_f32 v[92:93], v[92:93], v[84:85]
	v_pk_mul_f32 v[94:95], v[94:95], v[86:87]
	v_cvt_pk_bf16_f32 v192, v88, v89
	v_cvt_pk_bf16_f32 v193, v90, v91
	v_cvt_pk_bf16_f32 v194, v92, v93
	v_cvt_pk_bf16_f32 v195, v94, v95
	v_add_u32_e32 v245, 0x58000, v196
	global_store_dwordx4 v245, v[192:195], s[100:101]
	s_waitcnt lgkmcnt(1)
	v_lshlrev_b32_e32 v80, 16, v72
	v_and_b32_e32 v81, 0xffff0000, v72
	v_lshlrev_b32_e32 v82, 16, v73
	v_and_b32_e32 v83, 0xffff0000, v73
	v_lshlrev_b32_e32 v84, 16, v74
	v_and_b32_e32 v85, 0xffff0000, v74
	v_lshlrev_b32_e32 v86, 16, v75
	v_and_b32_e32 v87, 0xffff0000, v75
	s_waitcnt vmcnt(11)
	v_lshlrev_b32_e32 v88, 16, v200
	v_and_b32_e32 v89, 0xffff0000, v200
	v_lshlrev_b32_e32 v90, 16, v201
	v_and_b32_e32 v91, 0xffff0000, v201
	v_lshlrev_b32_e32 v92, 16, v202
	v_and_b32_e32 v93, 0xffff0000, v202
	v_lshlrev_b32_e32 v94, 16, v203
	v_and_b32_e32 v95, 0xffff0000, v203
	v_pk_mul_f32 v[88:89], v[88:89], v[80:81]
	v_pk_mul_f32 v[90:91], v[90:91], v[82:83]
	v_pk_mul_f32 v[92:93], v[92:93], v[84:85]
	v_pk_mul_f32 v[94:95], v[94:95], v[86:87]
	v_cvt_pk_bf16_f32 v200, v88, v89
	v_cvt_pk_bf16_f32 v201, v90, v91
	v_cvt_pk_bf16_f32 v202, v92, v93
	v_cvt_pk_bf16_f32 v203, v94, v95
	v_add_u32_e32 v244, 0x70000, v196
	global_store_dwordx4 v244, v[200:203], s[100:101]
	s_waitcnt lgkmcnt(0)
	v_lshlrev_b32_e32 v80, 16, v76
	v_and_b32_e32 v81, 0xffff0000, v76
	v_lshlrev_b32_e32 v82, 16, v77
	v_and_b32_e32 v83, 0xffff0000, v77
	v_lshlrev_b32_e32 v84, 16, v78
	v_and_b32_e32 v85, 0xffff0000, v78
	v_lshlrev_b32_e32 v86, 16, v79
	v_and_b32_e32 v87, 0xffff0000, v79
	s_waitcnt vmcnt(11)
	v_lshlrev_b32_e32 v88, 16, v204
	v_and_b32_e32 v89, 0xffff0000, v204
	v_lshlrev_b32_e32 v90, 16, v205
	v_and_b32_e32 v91, 0xffff0000, v205
	v_lshlrev_b32_e32 v92, 16, v206
	v_and_b32_e32 v93, 0xffff0000, v206
	v_lshlrev_b32_e32 v94, 16, v207
	v_and_b32_e32 v95, 0xffff0000, v207
	v_pk_mul_f32 v[88:89], v[88:89], v[80:81]
	v_pk_mul_f32 v[90:91], v[90:91], v[82:83]
	v_pk_mul_f32 v[92:93], v[92:93], v[84:85]
	v_pk_mul_f32 v[94:95], v[94:95], v[86:87]
	v_cvt_pk_bf16_f32 v204, v88, v89
	v_cvt_pk_bf16_f32 v205, v90, v91
	v_cvt_pk_bf16_f32 v206, v92, v93
	v_cvt_pk_bf16_f32 v207, v94, v95
	v_add_u32_e32 v245, 0x78000, v196
	global_store_dwordx4 v245, v[204:207], s[100:101]
	s_barrier
	s_nop 1
	s_branch .Lp3b_912n
